# plus phase-12 split-K minis overlapped with phase 13 through a flag, za block index mirrored to balance phase 6
# speedup vs baseline: 1.0499x; 1.0005x over previous
.LBB0_8:
	s_and_b32 s98, 1, s41
	s_cselect_b64 s[0:1], -1, 0
	s_and_b64 vcc, exec, s[0:1]
	s_mov_b64 s[0:1], -1
	s_cmp_eq_u32 s41, 26
	s_cbranch_scc1 .Ld_2627
	s_cmp_eq_u32 s41, 27
	s_cbranch_scc0 .Ld_not2627
.Ld_2627:
	v_readlane_b32 s2, v255, 20
	v_readlane_b32 s3, v250, 0
	s_nop 3
	s_cmp_eq_u32 s2, 0
	s_cbranch_scc1 .Ld_no
	s_cmp_lt_u32 s3, 44
	s_cbranch_scc0 .Ld_no
	s_cmp_eq_u32 s41, 26
	s_cbranch_scc1 .Lprobe_run
	s_branch .LBB0_504
.Ld_not2627:
	s_cmp_eq_u32 s41, 10
	s_cbranch_scc0 .Ld_no
	v_readlane_b32 s2, v255, 20
	v_readlane_b32 s3, v250, 0
	s_nop 3
	s_cmp_eq_u32 s2, 0
	s_cbranch_scc1 .Ld_no
	s_sub_u32 s3, s3, 0xe0
	s_cmp_lt_u32 s3, 28
	s_cbranch_scc0 .Ld_no
	s_and_b32 s2, s3, 7
	s_lshr_b32 s25, s3, 3
	s_mul_i32 s33, s2, 3
	s_add_i32 s33, s33, 4
	s_lshl_b32 s3, s2, 2
	s_cmp_lt_u32 s2, 4
	s_cselect_b32 s3, s3, s33
	s_add_i32 s3, s3, s25
	s_lshl_b32 s25, s2, 3
	s_add_i32 s25, s25, 8
	s_and_b32 s33, s3, 7
	s_add_i32 s25, s25, s33
	s_lshr_b32 s33, s3, 3
	s_cmp_eq_u32 s2, 7
	s_cselect_b32 s25, 64, s25
	s_cselect_b32 s33, s3, s33
	v_writelane_b32 v253, s25, 43
	v_writelane_b32 v253, s33, 49
	s_lshl_b32 s2, s25, 19
	s_add_u32 s2, s2, 0xc300000
	s_add_u32 s2, s62, s2
	s_addc_u32 s3, s63, 0
	v_writelane_b32 v253, s2, 52
	v_writelane_b32 v253, s3, 53
	s_add_u32 s2, s2, 0x40000
	s_addc_u32 s3, s3, 0
	v_writelane_b32 v253, s2, 54
	v_writelane_b32 v253, s3, 55
	s_lshl_b32 s2, s33, 19
	s_add_u32 s2, s2, 0xe380000
	s_add_u32 s2, s62, s2
	s_addc_u32 s3, s63, 0
	v_writelane_b32 v253, s2, 56
	v_writelane_b32 v253, s3, 57
	s_add_u32 s2, s2, 0x40000
	s_addc_u32 s3, s3, 0
	v_writelane_b32 v253, s2, 50
	v_writelane_b32 v253, s3, 51
	s_add_u32 s2, s2, 0x80
	s_addc_u32 s3, s3, 0
	v_writelane_b32 v253, s2, 58
	v_writelane_b32 v253, s3, 59
	v_mov_b64_e32 v[134:135], 0
	v_mov_b64_e32 v[248:249], -1
	s_branch .Lprobe_run

.Lprobe_run:
	v_mov_b32_e32 v142, v160
	s_cmp_gt_u32 s41, 1
	s_cbranch_scc0 .LBB0_13
	s_ashr_i32 s25, s41, 1
	s_cmp_eq_u32 s41, 10
	s_cselect_b32 s25, 4, s25
	s_cmp_eq_u32 s41, 26
	s_cselect_b32 s25, 12, s25
	s_cmp_lt_i32 s25, 11
	s_cbranch_scc1 .LBB0_69
	s_cmp_lg_u32 s25, 11
	s_cselect_b64 s[2:3], -1, 0
	s_cbranch_execz .LBB0_70
	s_branch .LBB0_71

.LBB0_71:
	s_andn2_b64 vcc, exec, s[2:3]
	v_writelane_b32 v255, s44, 0
	s_nop 1
	v_writelane_b32 v255, s45, 1
	v_writelane_b32 v255, s25, 2
	s_cbranch_vccnz .LBB0_424
	s_cmp_eq_u32 s25, 7
	s_cselect_b64 s[76:77], -1, 0
	v_writelane_b32 v255, s76, 3
	s_cmp_lt_i32 s25, 7
	s_nop 0
	v_writelane_b32 v255, s77, 4
	s_cbranch_scc1 .LBB0_79
	s_cmp_gt_i32 s25, 9
	s_cbranch_scc0 .LBB0_93
	s_cmp_gt_i32 s25, 11
	s_cbranch_scc0 .LBB0_111
	s_cmp_gt_i32 s25, 12
	s_mov_b64 s[74:75], -1
	s_cbranch_scc0 .LBB0_112
	s_cmp_eq_u32 s25, 13
	s_cbranch_scc0 .LBB0_120
	s_waitcnt vmcnt(0)
	v_ashrrev_i32_e32 v2, 6, v142
	v_readlane_b32 s0, v254, 0
	v_readlane_b32 s2, v255, 20
	s_nop 3
	s_sub_i32 s3, s0, 0x160
	s_cmp_lg_u32 s2, 0
	s_cselect_b32 s0, s3, s0
	v_add_u32_e32 v18, s0, v2
	s_movk_i32 s0, 0x4100
	v_cmp_gt_i32_e32 vcc, s0, v18
	s_and_saveexec_b64 s[0:1], vcc
	s_cbranch_execz .LBB0_119
	v_lshlrev_b32_e32 v3, 2, v142
	v_and_b32_e32 v4, 0xfc, v3
	v_readlane_b32 s2, v253, 45
	v_lshlrev_b32_e32 v0, 1, v4
	v_readlane_b32 s3, v253, 46
	s_mov_b64 s[20:21], 0
	v_lshlrev_b32_e32 v30, 2, v4
	v_lshl_add_u64 v[20:21], s[2:3], 0, v[0:1]
	v_readlane_b32 s2, v251, 24
	v_readlane_b32 s3, v251, 25
	s_nop 1
	v_lshl_add_u64 v[22:23], s[2:3], 0, v[0:1]
	v_readlane_b32 s2, v251, 9
	v_readlane_b32 s3, v251, 10
	s_nop 1
	v_lshl_add_u64 v[24:25], s[2:3], 0, v[0:1]
	s_movk_i32 s2, 0x80
	v_bfrev_b32_e32 v0, 0.5
	v_bitop3_b32 v33, v3, s2, v0 bitop3:0x6c
	v_bitop3_b32 v60, v3, 64, v0 bitop3:0x6c
	v_bitop3_b32 v61, v3, 32, v0 bitop3:0x6c
	v_bitop3_b32 v62, v3, 16, v0 bitop3:0x6c
	v_bitop3_b32 v63, v3, 8, v0 bitop3:0x6c
	v_bitop3_b32 v64, v3, 4, v0 bitop3:0x6c
	v_lshlrev_b32_e32 v0, 2, v4
	v_lshl_add_u64 v[26:27], s[52:53], 0, v[0:1]
	v_and_b32_e32 v0, 63, v142
	v_readlane_b32 s2, v253, 62
	v_lshlrev_b32_e32 v0, 3, v0
	v_readlane_b32 s3, v253, 63
	s_nop 1
	v_lshl_add_u64 v[28:29], s[2:3], 0, v[0:1]
	v_readlane_b32 s2, v254, 1
	v_readlane_b32 s3, v255, 20
	s_nop 3
	s_sub_i32 s22, s2, 0x160
	s_cmp_lg_u32 s3, 0
	s_cselect_b32 s2, s22, s2
	v_add_u32_e32 v0, s2, v2
	s_branch .LBB0_81

.LBB0_80:
	s_or_b64 exec, exec, s[2:3]
	v_readlane_b32 s2, v254, 57
	v_readlane_b32 s3, v255, 20
	s_nop 3
	s_cmp_lg_u32 s3, 0
	s_cselect_b32 s2, 0x6a0, s2
	s_movk_i32 s3, 0x40ff
	v_add_u32_e32 v18, s2, v18
	v_cmp_lt_i32_e32 vcc, s3, v18
	s_or_b64 s[20:21], vcc, s[20:21]
	v_add_u32_e32 v0, s2, v0
	s_andn2_b64 exec, exec, s[20:21]
	s_cbranch_execz .LBB0_119
.LBB0_81:
	v_readlane_b32 s2, v251, 22
	v_ashrrev_i32_e32 v19, 31, v18
	v_readlane_b32 s3, v251, 23
	s_waitcnt vmcnt(0)
	v_lshlrev_b64 v[2:3], 11, v[18:19]
	v_lshl_add_u64 v[6:7], v[20:21], 0, v[2:3]
	v_lshl_add_u64 v[4:5], v[18:19], 2, s[2:3]
	global_load_dword v32, v[4:5], off
	global_load_dwordx2 v[40:41], v[6:7], off
	global_load_dwordx2 v[38:39], v[6:7], off offset:512
	global_load_dwordx2 v[36:37], v[6:7], off offset:1024
	global_load_dwordx2 v[34:35], v[6:7], off offset:1536
	s_movk_i32 s2, 0x3fff
	v_cmp_lt_i32_e32 vcc, s2, v18
	s_and_saveexec_b64 s[2:3], vcc
	s_xor_b64 s[2:3], exec, s[2:3]
	s_cbranch_execz .LBB0_85
	v_readlane_b32 s22, v255, 20
	s_nop 3
	s_cmp_eq_u32 s22, 0
	s_cbranch_scc1 .Lfw13_done
	s_add_u32 s22, s62, 0xfa936b0
	s_addc_u32 s23, s63, 0
	s_mov_b32 s29, 0
.Lfw13:
	s_add_i32 s29, s29, 1
	s_cmp_gt_u32 s29, 0x800
	s_cbranch_scc1 .Lfw13_acq
	global_load_dword v120, v1, s[22:23] sc1
	s_waitcnt vmcnt(0)
	v_readfirstlane_b32 s28, v120
	s_nop 3
	s_cmp_ge_u32 s28, 44
	s_cbranch_scc1 .Lfw13_acq
	s_sleep 2
	s_branch .Lfw13
.Lfw13_acq:
	buffer_inv sc1
	s_waitcnt vmcnt(0)
.Lfw13_done:
	v_add_u32_e32 v4, 0xffffc000, v18
	v_mov_b32_e32 v5, v1
	v_lshlrev_b64 v[2:3], 11, v[0:1]
	v_lshlrev_b64 v[4:5], 11, v[4:5]
	v_mov_b32_e32 v54, 0
	v_lshl_add_u64 v[2:3], v[28:29], 0, v[2:3]
	v_lshl_add_u64 v[4:5], v[22:23], 0, v[4:5]
	s_mov_b32 s22, -4
	v_mov_b32_e32 v55, v54
	v_mov_b32_e32 v56, v54
	v_mov_b32_e32 v57, v54
	v_mov_b32_e32 v50, v54
	v_mov_b32_e32 v51, v54
	v_mov_b32_e32 v52, v54
	v_mov_b32_e32 v53, v54
	v_mov_b32_e32 v46, v54
	v_mov_b32_e32 v47, v54
	v_mov_b32_e32 v48, v54
	v_mov_b32_e32 v49, v54
	v_mov_b32_e32 v42, v54
	v_mov_b32_e32 v43, v54
	v_mov_b32_e32 v44, v54
	v_mov_b32_e32 v45, v54
	s_mov_b32 s25, 0xfff00000
	s_mov_b32 s31, 0xfff80000

.LBB0_213:
	v_readlane_b32 s0, v251, 28
	v_readlane_b32 s22, v251, 31
	s_nop 1
	s_sub_i32 s0, s22, s0
	s_sub_i32 s0, s0, 0x200
	s_nop 1
	v_add_u32_e32 v90, s0, v142
	s_mov_b32 s0, 0x20400
	v_cmp_gt_i32_e32 vcc, s0, v90
	v_readlane_b32 s0, v254, 6
	v_readlane_b32 s22, v254, 7
	s_nop 1
	s_sub_i32 s0, s22, s0
	s_sub_i32 s0, s0, 0x1000
	s_nop 1
	v_lshl_add_u32 v91, v142, 3, s0
	s_and_saveexec_b64 s[0:1], vcc
	v_readlane_b32 s22, v251, 29
	v_readlane_b32 s23, v251, 30
	s_cbranch_execz .LBB0_223
	v_readlane_b32 s2, v254, 6
	v_readlane_b32 s3, v254, 7
	s_nop 1
	s_sub_i32 s2, s3, s2
	s_sub_i32 s2, s2, 0x1000
	s_mov_b64 s[38:39], 0
	v_mov_b32_e32 v93, v90
	v_lshl_add_u32 v92, v142, 3, s2
	s_branch .LBB0_216

.LBB0_290:
	s_and_b64 s[2:3], s[76:77], exec
	s_cselect_b32 s33, 8, 4
	s_lshl_b32 s36, s33, 6
	v_readlane_b32 s2, v255, 5
	v_readlane_b32 s3, v255, 20
	s_nop 3
	s_cmp_eq_u32 s2, 26
	s_cselect_b32 s2, 1, 0
	s_and_b32 s2, s2, s3
	s_cmp_lg_u32 s2, 0
	s_cselect_b32 s36, 0, s36
	s_waitcnt vmcnt(0)
	v_mov_b32_e32 v16, v160
	v_readlane_b32 s2, v250, 0
	s_cmp_ge_i32 s2, s36
	v_readfirstlane_b32 s37, v16
	s_mov_b64 s[22:23], -1
	s_cbranch_scc0 .LBB0_292
	v_readlane_b32 s2, v250, 0
	s_sub_i32 s22, s2, s36
	s_and_b64 s[2:3], s[76:77], exec
	s_cselect_b32 s2, 3, 2
	s_lshl_b32 s3, s28, s2
	s_cmp_lt_i32 s22, s3
	s_cselect_b64 s[20:21], -1, 0
	s_lshr_b32 s64, s22, s2
	s_lshl_b32 s2, s64, s2
	s_lshl_b32 s96, s64, 2
	s_sub_i32 s35, s22, s2
	s_lshl_b64 s[2:3], s[96:97], 7
	s_mov_b64 s[22:23], 0

.LBB0_301:
	s_and_b64 s[20:21], s[76:77], exec
	s_mov_b32 s20, 0x4100000
	s_cselect_b32 s20, s20, 0x6180000
	s_add_u32 s20, s62, s20
	v_writelane_b32 v255, s20, 8
	s_addc_u32 s20, s63, 0
	v_writelane_b32 v255, s20, 10
	s_and_b64 s[20:21], s[76:77], exec
	s_mov_b32 s20, 0xe380000
	s_cselect_b32 s20, s20, 0x8200000
	s_add_u32 s20, s62, s20
	s_addc_u32 s21, s63, 0
	s_add_i32 m0, s43, 0x18000
	v_lshl_add_u64 v[2:3], v[2:3], 0, s[26:27]
	s_waitcnt vmcnt(4)
	s_barrier
	global_load_lds_dwordx4 v[2:3], off
	v_lshl_add_u64 v[2:3], v[4:5], 0, s[26:27]
	s_add_i32 m0, s43, 0x1a000
	s_add_i32 s66, s43, 0x8000
	global_load_lds_dwordx4 v[2:3], off
	v_lshl_add_u64 v[2:3], v[6:7], 0, s[26:27]
	s_mov_b32 m0, s66
	s_add_i32 s67, s43, 0xa000
	global_load_lds_dwordx4 v[2:3], off
	v_lshl_add_u64 v[2:3], v[8:9], 0, s[26:27]
	s_mov_b32 m0, s67
	v_lshrrev_b32_e32 v21, 1, v16
	global_load_lds_dwordx4 v[2:3], off
	s_add_i32 m0, s43, 0x1c000
	v_lshl_add_u64 v[2:3], v[10:11], 0, s[26:27]
	global_load_lds_dwordx4 v[2:3], off
	v_lshl_add_u64 v[2:3], v[12:13], 0, s[26:27]
	s_add_i32 m0, s43, 0x1e000
	v_and_b32_e32 v21, 24, v21
	global_load_lds_dwordx4 v[2:3], off
	v_and_b32_e32 v20, 15, v16
	v_lshlrev_b32_e32 v22, 1, v21
	v_lshlrev_b32_e32 v16, 2, v16
	v_cvt_f32_ubyte0_e32 v3, s33
	v_lshl_or_b32 v141, s0, 6, v20
	v_lshl_or_b32 v20, v20, 6, v22
	s_lshl_b32 s0, s0, 13
	v_and_b32_e32 v16, 32, v16
	v_rcp_iflag_f32_e32 v3, v3
	v_writelane_b32 v255, s20, 12
	v_bitop3_b32 v22, v20, s0, v16 bitop3:0xde
	s_lshl_b32 s0, s1, 5
	v_writelane_b32 v255, s21, 13
	s_and_b32 s20, s0, 0x60
	s_lshl_b32 s0, s20, 7
	v_bitop3_b32 v143, v20, s0, v16 bitop3:0xde
	s_and_b64 s[0:1], s[76:77], exec
	v_mul_f32_e32 v3, 0x4f7ffffe, v3
	s_cselect_b32 s69, 3, 2
	v_cvt_u32_f32_e32 v3, v3
	s_lshl_b32 s0, s28, s69
	v_writelane_b32 v255, s0, 14
	v_readlane_b32 s0, v255, 5
	v_readlane_b32 s1, v255, 20
	s_nop 3
	s_cmp_eq_u32 s0, 25
	s_cselect_b32 s0, 1, 0
	s_and_b32 s0, s0, s1
	s_cmp_lg_u32 s0, 0
	s_cbranch_scc0 .Lm2_skip
	s_mov_b32 s0, 0
	v_writelane_b32 v255, s0, 14
.Lm2_skip:
	s_and_b64 s[0:1], s[76:77], exec
	s_cselect_b32 s0, 6, 5
	s_lshl_b32 s72, s33, 3
	v_readfirstlane_b32 s1, v3
	v_cvt_f32_ubyte0_e32 v3, s72
	v_rcp_iflag_f32_e32 v3, v3
	v_writelane_b32 v255, s0, 16
	s_or_b32 s0, s72, 1
	v_writelane_b32 v255, s0, 17
	v_mul_f32_e32 v3, 0x4f7ffffe, v3
	s_sub_i32 s0, 0, s33
	v_cvt_u32_f32_e32 v3, v3
	s_mul_i32 s0, s0, s1
	s_mul_hi_u32 s0, s1, s0
	s_add_i32 s0, s1, s0
	v_add_u32_e32 v0, v15, v0
	v_writelane_b32 v255, s0, 18
	s_sub_i32 s0, 0, s72
	v_readfirstlane_b32 s1, v3
	v_add_lshl_u32 v0, v0, v14, 1
	s_waitcnt vmcnt(6)
	s_mul_i32 s0, s0, s1
	v_lshl_add_u64 v[152:153], s[96:97], 0, v[0:1]
	v_add_u32_e32 v0, v19, v17
	v_or_b32_e32 v2, s20, v21
	s_mul_hi_u32 s0, s1, s0
	v_add_lshl_u32 v0, v0, v18, 1
	s_mov_b32 s38, 0
	s_mov_b32 s37, s97
	v_cndmask_b32_e64 v158, 0, 1, s[76:77]
	s_add_i32 s75, s1, s0
	v_lshl_add_u64 v[154:155], s[96:97], 0, v[0:1]
	v_add_u32_e32 v159, 0, v22
	v_lshlrev_b32_e32 v167, 1, v2
	s_barrier
	s_branch .LBB0_304

.LBB0_503:
.LBB0_504:
	s_setprio 0
	s_add_i32 s33, s41, 1
	s_cmp_eq_u32 s41, 10
	s_cbranch_scc1 .LBB0_571
	s_cmp_eq_u32 s41, 26
	s_cbranch_scc0 .Lsig_no
	s_waitcnt vmcnt(0) lgkmcnt(0)
	s_barrier
	v_readlane_b32 s2, v250, 3
	v_readlane_b32 s3, v250, 4
	s_mov_b64 s[0:1], exec
	s_nop 1
	s_and_b64 s[2:3], s[0:1], s[2:3]
	s_mov_b64 exec, s[2:3]
	s_cbranch_execz .Lsig_skip
	buffer_wbl2 sc1
	s_waitcnt vmcnt(0)
	s_add_u32 s2, s62, 0xfa936b0
	s_addc_u32 s3, s63, 0
	v_mov_b32_e32 v2, 1
	s_nop 1
	global_atomic_add v1, v2, s[2:3]
	s_waitcnt vmcnt(0)
.Lsig_skip:
	s_mov_b64 exec, s[0:1]
	s_branch .LBB0_571
.Lsig_no:
	s_cmp_ge_i32 s33, s40
	s_cbranch_scc1 .LBB0_571
